# v5: + P6 V transposes issue their 8 row loads together (one wait) instead of 8 dependent load-wait-ds_write round trips
# speedup vs baseline: 1.1090x; 1.0078x over previous
.LBB0_342:
	s_ashr_i32 s17, s16, 31
	s_lshl_b64 s[16:17], s[16:17], 19
	s_add_u32 s18, s18, s16
	s_addc_u32 s19, s19, s17
	s_add_u32 s16, s20, s16
	s_addc_u32 s17, s21, s17
	s_lshr_b32 s20, 0x1000, s22
	s_and_b32 s21, s35, 0xfc0
	s_add_i32 s20, s20, -1
	s_and_b32 s20, s20, s21
	s_sub_i32 s23, 12, s22
	v_add_u32_e32 v29, s20, v0
	s_lshr_b32 s23, s21, s23
	v_lshl_add_u64 v[18:19], s[18:19], 0, v[136:137]
	v_lshlrev_b32_e32 v30, s22, v29
	v_add_u32_e32 v30, s23, v30
	v_ashrrev_i32_e32 v31, 31, v30
	v_lshlrev_b64 v[30:31], 7, v[30:31]
	v_lshl_add_u64 v[30:31], v[18:19], 0, v[30:31]
	global_load_dwordx4 v[64:67], v[30:31], off
	v_add_lshl_u32 v30, v29, 8, s22
	v_add_u32_e32 v30, s23, v30
	v_ashrrev_i32_e32 v31, 31, v30
	v_lshlrev_b64 v[30:31], 7, v[30:31]
	v_lshl_add_u64 v[30:31], v[18:19], 0, v[30:31]
	global_load_dwordx4 v[68:71], v[30:31], off
	v_add_lshl_u32 v30, v29, 16, s22
	v_add_u32_e32 v30, s23, v30
	v_ashrrev_i32_e32 v31, 31, v30
	v_lshlrev_b64 v[30:31], 7, v[30:31]
	v_lshl_add_u64 v[30:31], v[18:19], 0, v[30:31]
	global_load_dwordx4 v[72:75], v[30:31], off
	v_add_lshl_u32 v30, v29, 24, s22
	v_add_u32_e32 v30, s23, v30
	v_ashrrev_i32_e32 v31, 31, v30
	v_lshlrev_b64 v[30:31], 7, v[30:31]
	v_lshl_add_u64 v[30:31], v[18:19], 0, v[30:31]
	global_load_dwordx4 v[76:79], v[30:31], off
	v_add_lshl_u32 v30, v29, 32, s22
	v_add_u32_e32 v30, s23, v30
	v_ashrrev_i32_e32 v31, 31, v30
	v_lshlrev_b64 v[30:31], 7, v[30:31]
	v_lshl_add_u64 v[30:31], v[18:19], 0, v[30:31]
	global_load_dwordx4 v[80:83], v[30:31], off
	v_add_lshl_u32 v30, v29, 40, s22
	v_add_u32_e32 v30, s23, v30
	v_ashrrev_i32_e32 v31, 31, v30
	v_lshlrev_b64 v[30:31], 7, v[30:31]
	v_lshl_add_u64 v[30:31], v[18:19], 0, v[30:31]
	global_load_dwordx4 v[84:87], v[30:31], off
	v_add_lshl_u32 v30, v29, 48, s22
	v_add_u32_e32 v30, s23, v30
	v_ashrrev_i32_e32 v31, 31, v30
	v_lshlrev_b64 v[30:31], 7, v[30:31]
	v_lshl_add_u64 v[30:31], v[18:19], 0, v[30:31]
	global_load_dwordx4 v[88:91], v[30:31], off
	v_add_lshl_u32 v30, v29, 56, s22
	v_add_u32_e32 v30, s23, v30
	v_ashrrev_i32_e32 v31, 31, v30
	v_lshlrev_b64 v[30:31], 7, v[30:31]
	v_lshl_add_u64 v[30:31], v[18:19], 0, v[30:31]
	global_load_dwordx4 v[92:95], v[30:31], off
	s_lshl_b32 s18, s21, 1
	s_add_u32 s16, s16, s18
	s_addc_u32 s17, s17, 0
	s_add_i32 s27, s27, s28
	s_add_i32 s35, s35, s36
	s_cmpk_gt_i32 s27, 0x1bff
	v_lshl_add_u64 v[18:19], s[16:17], 0, v[136:137]
	s_waitcnt vmcnt(0) lgkmcnt(0)
	ds_write_b128 v28, v[64:67]
	ds_write_b128 v28, v[68:71] offset:1152
	ds_write_b128 v28, v[72:75] offset:2304
	ds_write_b128 v28, v[76:79] offset:3456
	ds_write_b128 v28, v[80:83] offset:4608
	ds_write_b128 v28, v[84:87] offset:5760
	ds_write_b128 v28, v[88:91] offset:6912
	ds_write_b128 v28, v[92:95] offset:8064
	s_waitcnt vmcnt(0) lgkmcnt(0)
	ds_read_u16 v29, v21
	ds_read_u16 v30, v21 offset:144
	ds_read_u16 v31, v21 offset:288
	ds_read_u16 v34, v21 offset:432
	ds_read_u16 v32, v21 offset:2304
	ds_read_u16 v35, v21 offset:2448
	ds_read_u16 v33, v21 offset:2592
	ds_read_u16 v36, v21 offset:2736
	s_waitcnt lgkmcnt(4)
	v_perm_b32 v31, v34, v31, s85
	v_perm_b32 v30, v30, v29, s85
	s_waitcnt lgkmcnt(2)
	v_perm_b32 v32, v35, v32, s85
	v_lshl_add_u64 v[34:35], v[18:19], 0, v[2:3]
	s_waitcnt lgkmcnt(0)
	v_perm_b32 v33, v36, v33, s85
	flat_store_dwordx4 v[34:35], v[30:33]
	ds_read_u16 v29, v1
	ds_read_u16 v30, v1 offset:144
	ds_read_u16 v31, v1 offset:288
	ds_read_u16 v34, v1 offset:432
	ds_read_u16 v32, v1 offset:2304
	ds_read_u16 v35, v1 offset:2448
	ds_read_u16 v33, v1 offset:2592
	ds_read_u16 v36, v1 offset:2736
	s_waitcnt lgkmcnt(0)
	v_perm_b32 v31, v34, v31, s85
	v_perm_b32 v30, v30, v29, s85
	v_perm_b32 v32, v35, v32, s85
	v_lshl_add_u64 v[34:35], v[18:19], 0, v[4:5]
	v_perm_b32 v33, v36, v33, s85
	flat_store_dwordx4 v[34:35], v[30:33]
	ds_read_u16 v29, v22
	ds_read_u16 v30, v22 offset:144
	ds_read_u16 v31, v22 offset:288
	ds_read_u16 v34, v22 offset:432
	ds_read_u16 v32, v22 offset:2304
	ds_read_u16 v35, v22 offset:2448
	ds_read_u16 v33, v22 offset:2592
	ds_read_u16 v36, v22 offset:2736
	s_waitcnt lgkmcnt(0)
	v_perm_b32 v31, v34, v31, s85
	v_perm_b32 v30, v30, v29, s85
	v_perm_b32 v32, v35, v32, s85
	v_lshl_add_u64 v[34:35], v[18:19], 0, v[6:7]
	v_perm_b32 v33, v36, v33, s85
	flat_store_dwordx4 v[34:35], v[30:33]
	ds_read_u16 v29, v23
	ds_read_u16 v30, v23 offset:144
	ds_read_u16 v31, v23 offset:288
	ds_read_u16 v34, v23 offset:432
	ds_read_u16 v32, v23 offset:2304
	ds_read_u16 v35, v23 offset:2448
	ds_read_u16 v33, v23 offset:2592
	ds_read_u16 v36, v23 offset:2736
	s_waitcnt lgkmcnt(0)
	v_perm_b32 v31, v34, v31, s85
	v_perm_b32 v30, v30, v29, s85
	v_perm_b32 v32, v35, v32, s85
	v_lshl_add_u64 v[34:35], v[18:19], 0, v[8:9]
	v_perm_b32 v33, v36, v33, s85
	flat_store_dwordx4 v[34:35], v[30:33]
	ds_read_u16 v29, v24
	ds_read_u16 v30, v24 offset:144
	ds_read_u16 v31, v24 offset:288
	ds_read_u16 v34, v24 offset:432
	ds_read_u16 v32, v24 offset:2304
	ds_read_u16 v35, v24 offset:2448
	ds_read_u16 v33, v24 offset:2592
	ds_read_u16 v36, v24 offset:2736
	s_waitcnt lgkmcnt(0)
	v_perm_b32 v31, v34, v31, s85
	v_perm_b32 v30, v30, v29, s85
	v_perm_b32 v32, v35, v32, s85
	v_lshl_add_u64 v[34:35], v[18:19], 0, v[10:11]
	v_perm_b32 v33, v36, v33, s85
	flat_store_dwordx4 v[34:35], v[30:33]
	ds_read_u16 v29, v25
	ds_read_u16 v30, v25 offset:144
	ds_read_u16 v31, v25 offset:288
	ds_read_u16 v34, v25 offset:432
	ds_read_u16 v32, v25 offset:2304
	ds_read_u16 v35, v25 offset:2448
	ds_read_u16 v33, v25 offset:2592
	ds_read_u16 v36, v25 offset:2736
	s_waitcnt lgkmcnt(0)
	v_perm_b32 v31, v34, v31, s85
	v_perm_b32 v30, v30, v29, s85
	v_perm_b32 v32, v35, v32, s85
	v_lshl_add_u64 v[34:35], v[18:19], 0, v[12:13]
	v_perm_b32 v33, v36, v33, s85
	flat_store_dwordx4 v[34:35], v[30:33]
	ds_read_u16 v29, v26
	ds_read_u16 v30, v26 offset:144
	ds_read_u16 v31, v26 offset:288
	ds_read_u16 v34, v26 offset:432
	ds_read_u16 v32, v26 offset:2304
	ds_read_u16 v35, v26 offset:2448
	ds_read_u16 v33, v26 offset:2592
	ds_read_u16 v36, v26 offset:2736
	s_waitcnt lgkmcnt(0)
	v_perm_b32 v31, v34, v31, s85
	v_perm_b32 v30, v30, v29, s85
	v_perm_b32 v32, v35, v32, s85
	v_lshl_add_u64 v[34:35], v[18:19], 0, v[14:15]
	v_perm_b32 v33, v36, v33, s85
	flat_store_dwordx4 v[34:35], v[30:33]
	ds_read_u16 v29, v27
	ds_read_u16 v30, v27 offset:144
	ds_read_u16 v31, v27 offset:288
	ds_read_u16 v34, v27 offset:432
	ds_read_u16 v32, v27 offset:2304
	ds_read_u16 v35, v27 offset:2448
	ds_read_u16 v33, v27 offset:2592
	ds_read_u16 v36, v27 offset:2736
	s_waitcnt lgkmcnt(0)
	v_perm_b32 v31, v34, v31, s85
	v_perm_b32 v30, v30, v29, s85
	v_perm_b32 v32, v35, v32, s85
	v_lshl_add_u64 v[18:19], v[18:19], 0, v[16:17]
	v_perm_b32 v33, v36, v33, s85
	flat_store_dwordx4 v[18:19], v[30:33]
	s_waitcnt lgkmcnt(0)
	s_cbranch_scc1 .LBB0_355
